# producer waves at s_setprio 2 inside the GEMM streams
# speedup vs baseline: 1.0137x; 1.0064x over previous
.Lpc_prod_5:
	s_setprio 2

.Lpc_pgo_5:
	s_nop 0
	s_sub_u32 s26, s26, s98
	s_subb_u32 s27, s27, 0
	s_sub_u32 s38, s38, s99
	s_subb_u32 s39, s39, 0
	s_mov_b32 vcc_hi, vcc_lo
	s_add_u32 m0, s30, -1
	s_and_b32 vcc_hi, vcc_hi, m0
	s_lshl_b32 vcc_hi, vcc_hi, 7
	v_add_u32_e32 v20, vcc_hi, v4
	v_add_u32_e32 v21, vcc_hi, v5
	v_add_u32_e32 v22, vcc_hi, v6
	v_add_u32_e32 v23, vcc_hi, v7
	v_add_u32_e32 v24, vcc_hi, v8
	v_add_u32_e32 v25, vcc_hi, v9
	v_add_u32_e32 v26, vcc_hi, v10
	v_add_u32_e32 v27, vcc_hi, v11
	v_add_u32_e32 v28, vcc_hi, v12
	v_add_u32_e32 v29, vcc_hi, v13
	v_add_u32_e32 v30, vcc_hi, v14
	v_add_u32_e32 v31, vcc_hi, v15
	v_add_u32_e32 v32, vcc_hi, v16
	v_add_u32_e32 v33, vcc_hi, v17
	v_add_u32_e32 v34, vcc_hi, v18
	v_add_u32_e32 v35, vcc_hi, v19
	s_add_u32 vcc_lo, vcc_lo, 1
	s_barrier
	s_add_u32 m0, s100, 0x0
	s_nop 0
	global_load_lds_dwordx4 v20, s[26:27]
	s_add_u32 m0, s100, 0x400
	s_nop 0
	global_load_lds_dwordx4 v21, s[26:27]
	s_add_u32 m0, s100, 0x1000
	s_nop 0
	global_load_lds_dwordx4 v22, s[26:27]
	s_add_u32 m0, s100, 0x1400
	s_nop 0
	global_load_lds_dwordx4 v23, s[26:27]
	s_add_u32 m0, s100, 0x2000
	s_nop 0
	global_load_lds_dwordx4 v24, s[26:27]
	s_add_u32 m0, s100, 0x2400
	s_nop 0
	global_load_lds_dwordx4 v25, s[26:27]
	s_add_u32 m0, s100, 0x3000
	s_nop 0
	global_load_lds_dwordx4 v26, s[26:27]
	s_add_u32 m0, s100, 0x3400
	s_nop 0
	global_load_lds_dwordx4 v27, s[26:27]
	s_waitcnt vmcnt(8)
	s_barrier
	s_add_u32 m0, s100, 0x4000
	s_nop 0
	global_load_lds_dwordx4 v28, s[38:39]
	s_add_u32 m0, s100, 0x4400
	s_nop 0
	global_load_lds_dwordx4 v29, s[38:39]
	s_add_u32 m0, s100, 0x5000
	s_nop 0
	global_load_lds_dwordx4 v30, s[38:39]
	s_add_u32 m0, s100, 0x5400
	s_nop 0
	global_load_lds_dwordx4 v31, s[38:39]
	s_add_u32 m0, s100, 0x6000
	s_nop 0
	global_load_lds_dwordx4 v32, s[38:39]
	s_add_u32 m0, s100, 0x6400
	s_nop 0
	global_load_lds_dwordx4 v33, s[38:39]
	s_add_u32 m0, s100, 0x7000
	s_nop 0
	global_load_lds_dwordx4 v34, s[38:39]
	s_add_u32 m0, s100, 0x7400
	s_nop 0
	global_load_lds_dwordx4 v35, s[38:39]
	s_mov_b32 vcc_hi, vcc_lo
	s_add_u32 m0, s30, -1
	s_and_b32 vcc_hi, vcc_hi, m0
	s_lshl_b32 vcc_hi, vcc_hi, 7
	v_add_u32_e32 v20, vcc_hi, v4
	v_add_u32_e32 v21, vcc_hi, v5
	v_add_u32_e32 v22, vcc_hi, v6
	v_add_u32_e32 v23, vcc_hi, v7
	v_add_u32_e32 v24, vcc_hi, v8
	v_add_u32_e32 v25, vcc_hi, v9
	v_add_u32_e32 v26, vcc_hi, v10
	v_add_u32_e32 v27, vcc_hi, v11
	v_add_u32_e32 v28, vcc_hi, v12
	v_add_u32_e32 v29, vcc_hi, v13
	v_add_u32_e32 v30, vcc_hi, v14
	v_add_u32_e32 v31, vcc_hi, v15
	v_add_u32_e32 v32, vcc_hi, v16
	v_add_u32_e32 v33, vcc_hi, v17
	v_add_u32_e32 v34, vcc_hi, v18
	v_add_u32_e32 v35, vcc_hi, v19
	s_add_u32 vcc_lo, vcc_lo, 1
	s_barrier
	s_add_u32 m0, s100, 0x8000
	s_nop 0
	global_load_lds_dwordx4 v20, s[26:27]
	s_add_u32 m0, s100, 0x8400
	s_nop 0
	global_load_lds_dwordx4 v21, s[26:27]
	s_add_u32 m0, s100, 0x9000
	s_nop 0
	global_load_lds_dwordx4 v22, s[26:27]
	s_add_u32 m0, s100, 0x9400
	s_nop 0
	global_load_lds_dwordx4 v23, s[26:27]
	s_add_u32 m0, s100, 0xa000
	s_nop 0
	global_load_lds_dwordx4 v24, s[26:27]
	s_add_u32 m0, s100, 0xa400
	s_nop 0
	global_load_lds_dwordx4 v25, s[26:27]
	s_add_u32 m0, s100, 0xb000
	s_nop 0
	global_load_lds_dwordx4 v26, s[26:27]
	s_add_u32 m0, s100, 0xb400
	s_nop 0
	global_load_lds_dwordx4 v27, s[26:27]
	s_waitcnt vmcnt(8)
	s_barrier
	s_add_u32 m0, s100, 0xc000
	s_nop 0
	global_load_lds_dwordx4 v28, s[38:39]
	s_add_u32 m0, s100, 0xc400
	s_nop 0
	global_load_lds_dwordx4 v29, s[38:39]
	s_add_u32 m0, s100, 0xd000
	s_nop 0
	global_load_lds_dwordx4 v30, s[38:39]
	s_add_u32 m0, s100, 0xd400
	s_nop 0
	global_load_lds_dwordx4 v31, s[38:39]
	s_add_u32 m0, s100, 0xe000
	s_nop 0
	global_load_lds_dwordx4 v32, s[38:39]
	s_add_u32 m0, s100, 0xe400
	s_nop 0
	global_load_lds_dwordx4 v33, s[38:39]
	s_add_u32 m0, s100, 0xf000
	s_nop 0
	global_load_lds_dwordx4 v34, s[38:39]
	s_add_u32 m0, s100, 0xf400
	s_nop 0
	global_load_lds_dwordx4 v35, s[38:39]
	s_add_u32 s24, s24, 0x100
	s_addc_u32 s25, s25, 0
	s_add_i32 s53, s53, 2
	s_cmp_le_i32 s53, s52
	s_cbranch_scc1 .Lpc_ptop_5
	s_setprio 0
	s_add_i32 s42, s42, 1
	s_mov_b32 s46, s44
	s_mov_b32 s47, s45
	s_cmp_eq_u32 s42, 3
	s_cbranch_scc0 .Lpc_pnd_5
	s_waitcnt vmcnt(0)
	s_branch .LBB0_165

.Lpc_pgo_2:
	s_nop 0
	s_sub_u32 s40, s40, s98
	s_subb_u32 s41, s41, 0
	s_sub_u32 s38, s38, s99
	s_subb_u32 s39, s39, 0
	s_bfe_u32 vcc_hi, s101, 0x80008
	s_add_u32 vcc_hi, vcc_hi, vcc_lo
	s_add_u32 m0, s42, -1
	s_and_b32 vcc_hi, vcc_hi, m0
	s_lshl_b32 vcc_hi, vcc_hi, 7
	v_add_u32_e32 v20, vcc_hi, v4
	v_add_u32_e32 v21, vcc_hi, v5
	v_add_u32_e32 v22, vcc_hi, v6
	v_add_u32_e32 v23, vcc_hi, v7
	v_add_u32_e32 v24, vcc_hi, v8
	v_add_u32_e32 v25, vcc_hi, v9
	v_add_u32_e32 v26, vcc_hi, v10
	v_add_u32_e32 v27, vcc_hi, v11
	v_add_u32_e32 v28, vcc_hi, v12
	v_add_u32_e32 v29, vcc_hi, v13
	v_add_u32_e32 v30, vcc_hi, v14
	v_add_u32_e32 v31, vcc_hi, v15
	v_add_u32_e32 v32, vcc_hi, v16
	v_add_u32_e32 v33, vcc_hi, v17
	v_add_u32_e32 v34, vcc_hi, v18
	v_add_u32_e32 v35, vcc_hi, v19
	s_add_u32 vcc_lo, vcc_lo, 1
	s_barrier
	s_add_u32 m0, s100, 0x0
	s_nop 0
	global_load_lds_dwordx4 v20, s[40:41]
	s_add_u32 m0, s100, 0x400
	s_nop 0
	global_load_lds_dwordx4 v21, s[40:41]
	s_add_u32 m0, s100, 0x1000
	s_nop 0
	global_load_lds_dwordx4 v22, s[40:41]
	s_add_u32 m0, s100, 0x1400
	s_nop 0
	global_load_lds_dwordx4 v23, s[40:41]
	s_add_u32 m0, s100, 0x2000
	s_nop 0
	global_load_lds_dwordx4 v24, s[40:41]
	s_add_u32 m0, s100, 0x2400
	s_nop 0
	global_load_lds_dwordx4 v25, s[40:41]
	s_add_u32 m0, s100, 0x3000
	s_nop 0
	global_load_lds_dwordx4 v26, s[40:41]
	s_add_u32 m0, s100, 0x3400
	s_nop 0
	global_load_lds_dwordx4 v27, s[40:41]
	s_waitcnt vmcnt(8)
	s_barrier
	s_add_u32 m0, s100, 0x4000
	s_nop 0
	global_load_lds_dwordx4 v28, s[38:39]
	s_add_u32 m0, s100, 0x4400
	s_nop 0
	global_load_lds_dwordx4 v29, s[38:39]
	s_add_u32 m0, s100, 0x5000
	s_nop 0
	global_load_lds_dwordx4 v30, s[38:39]
	s_add_u32 m0, s100, 0x5400
	s_nop 0
	global_load_lds_dwordx4 v31, s[38:39]
	s_add_u32 m0, s100, 0x6000
	s_nop 0
	global_load_lds_dwordx4 v32, s[38:39]
	s_add_u32 m0, s100, 0x6400
	s_nop 0
	global_load_lds_dwordx4 v33, s[38:39]
	s_add_u32 m0, s100, 0x7000
	s_nop 0
	global_load_lds_dwordx4 v34, s[38:39]
	s_add_u32 m0, s100, 0x7400
	s_nop 0
	global_load_lds_dwordx4 v35, s[38:39]
	s_bfe_u32 vcc_hi, s101, 0x80008
	s_add_u32 vcc_hi, vcc_hi, vcc_lo
	s_add_u32 m0, s42, -1
	s_and_b32 vcc_hi, vcc_hi, m0
	s_lshl_b32 vcc_hi, vcc_hi, 7
	v_add_u32_e32 v20, vcc_hi, v4
	v_add_u32_e32 v21, vcc_hi, v5
	v_add_u32_e32 v22, vcc_hi, v6
	v_add_u32_e32 v23, vcc_hi, v7
	v_add_u32_e32 v24, vcc_hi, v8
	v_add_u32_e32 v25, vcc_hi, v9
	v_add_u32_e32 v26, vcc_hi, v10
	v_add_u32_e32 v27, vcc_hi, v11
	v_add_u32_e32 v28, vcc_hi, v12
	v_add_u32_e32 v29, vcc_hi, v13
	v_add_u32_e32 v30, vcc_hi, v14
	v_add_u32_e32 v31, vcc_hi, v15
	v_add_u32_e32 v32, vcc_hi, v16
	v_add_u32_e32 v33, vcc_hi, v17
	v_add_u32_e32 v34, vcc_hi, v18
	v_add_u32_e32 v35, vcc_hi, v19
	s_add_u32 vcc_lo, vcc_lo, 1
	s_barrier
	s_add_u32 m0, s100, 0x8000
	s_nop 0
	global_load_lds_dwordx4 v20, s[40:41]
	s_add_u32 m0, s100, 0x8400
	s_nop 0
	global_load_lds_dwordx4 v21, s[40:41]
	s_add_u32 m0, s100, 0x9000
	s_nop 0
	global_load_lds_dwordx4 v22, s[40:41]
	s_add_u32 m0, s100, 0x9400
	s_nop 0
	global_load_lds_dwordx4 v23, s[40:41]
	s_add_u32 m0, s100, 0xa000
	s_nop 0
	global_load_lds_dwordx4 v24, s[40:41]
	s_add_u32 m0, s100, 0xa400
	s_nop 0
	global_load_lds_dwordx4 v25, s[40:41]
	s_add_u32 m0, s100, 0xb000
	s_nop 0
	global_load_lds_dwordx4 v26, s[40:41]
	s_add_u32 m0, s100, 0xb400
	s_nop 0
	global_load_lds_dwordx4 v27, s[40:41]
	s_waitcnt vmcnt(8)
	s_barrier
	s_add_u32 m0, s100, 0xc000
	s_nop 0
	global_load_lds_dwordx4 v28, s[38:39]
	s_add_u32 m0, s100, 0xc400
	s_nop 0
	global_load_lds_dwordx4 v29, s[38:39]
	s_add_u32 m0, s100, 0xd000
	s_nop 0
	global_load_lds_dwordx4 v30, s[38:39]
	s_add_u32 m0, s100, 0xd400
	s_nop 0
	global_load_lds_dwordx4 v31, s[38:39]
	s_add_u32 m0, s100, 0xe000
	s_nop 0
	global_load_lds_dwordx4 v32, s[38:39]
	s_add_u32 m0, s100, 0xe400
	s_nop 0
	global_load_lds_dwordx4 v33, s[38:39]
	s_add_u32 m0, s100, 0xf000
	s_nop 0
	global_load_lds_dwordx4 v34, s[38:39]
	s_add_u32 m0, s100, 0xf400
	s_nop 0
	global_load_lds_dwordx4 v35, s[38:39]
	s_add_u32 s34, s34, 0x100
	s_addc_u32 s35, s35, 0
	s_add_i32 s55, s55, 2
	s_cmp_le_i32 s55, s47
	s_cbranch_scc1 .Lpc_ptop_2
	s_setprio 0
	s_movk_i32 s55, 0x4000
	s_mov_b32 s53, s1
	s_mov_b32 s52, s3
	s_and_b64 vcc, exec, s[26:27]
	v_mov_b64_e32 v[146:147], v[142:143]
	v_mov_b64_e32 v[144:145], v[140:141]
	s_cbranch_vccz .Lpc_pnd_2
	s_waitcnt vmcnt(0)
	s_branch .LBB0_191

.Lpc_pgo_6:
	s_nop 0
	s_sub_u32 s26, s26, s98
	s_subb_u32 s27, s27, 0
	s_sub_u32 s38, s38, s99
	s_subb_u32 s39, s39, 0
	s_mov_b32 vcc_hi, vcc_lo
	s_add_u32 m0, s30, -1
	s_and_b32 vcc_hi, vcc_hi, m0
	s_lshl_b32 vcc_hi, vcc_hi, 7
	v_add_u32_e32 v20, vcc_hi, v4
	v_add_u32_e32 v21, vcc_hi, v5
	v_add_u32_e32 v22, vcc_hi, v6
	v_add_u32_e32 v23, vcc_hi, v7
	v_add_u32_e32 v24, vcc_hi, v8
	v_add_u32_e32 v25, vcc_hi, v9
	v_add_u32_e32 v26, vcc_hi, v10
	v_add_u32_e32 v27, vcc_hi, v11
	v_add_u32_e32 v28, vcc_hi, v12
	v_add_u32_e32 v29, vcc_hi, v13
	v_add_u32_e32 v30, vcc_hi, v14
	v_add_u32_e32 v31, vcc_hi, v15
	v_add_u32_e32 v32, vcc_hi, v16
	v_add_u32_e32 v33, vcc_hi, v17
	v_add_u32_e32 v34, vcc_hi, v18
	v_add_u32_e32 v35, vcc_hi, v19
	s_add_u32 vcc_lo, vcc_lo, 1
	s_barrier
	s_add_u32 m0, s100, 0x0
	s_nop 0
	global_load_lds_dwordx4 v20, s[26:27]
	s_add_u32 m0, s100, 0x400
	s_nop 0
	global_load_lds_dwordx4 v21, s[26:27]
	s_add_u32 m0, s100, 0x1000
	s_nop 0
	global_load_lds_dwordx4 v22, s[26:27]
	s_add_u32 m0, s100, 0x1400
	s_nop 0
	global_load_lds_dwordx4 v23, s[26:27]
	s_add_u32 m0, s100, 0x2000
	s_nop 0
	global_load_lds_dwordx4 v24, s[26:27]
	s_add_u32 m0, s100, 0x2400
	s_nop 0
	global_load_lds_dwordx4 v25, s[26:27]
	s_add_u32 m0, s100, 0x3000
	s_nop 0
	global_load_lds_dwordx4 v26, s[26:27]
	s_add_u32 m0, s100, 0x3400
	s_nop 0
	global_load_lds_dwordx4 v27, s[26:27]
	s_waitcnt vmcnt(8)
	s_barrier
	s_add_u32 m0, s100, 0x4000
	s_nop 0
	global_load_lds_dwordx4 v28, s[38:39]
	s_add_u32 m0, s100, 0x4400
	s_nop 0
	global_load_lds_dwordx4 v29, s[38:39]
	s_add_u32 m0, s100, 0x5000
	s_nop 0
	global_load_lds_dwordx4 v30, s[38:39]
	s_add_u32 m0, s100, 0x5400
	s_nop 0
	global_load_lds_dwordx4 v31, s[38:39]
	s_add_u32 m0, s100, 0x6000
	s_nop 0
	global_load_lds_dwordx4 v32, s[38:39]
	s_add_u32 m0, s100, 0x6400
	s_nop 0
	global_load_lds_dwordx4 v33, s[38:39]
	s_add_u32 m0, s100, 0x7000
	s_nop 0
	global_load_lds_dwordx4 v34, s[38:39]
	s_add_u32 m0, s100, 0x7400
	s_nop 0
	global_load_lds_dwordx4 v35, s[38:39]
	s_mov_b32 vcc_hi, vcc_lo
	s_add_u32 m0, s30, -1
	s_and_b32 vcc_hi, vcc_hi, m0
	s_lshl_b32 vcc_hi, vcc_hi, 7
	v_add_u32_e32 v20, vcc_hi, v4
	v_add_u32_e32 v21, vcc_hi, v5
	v_add_u32_e32 v22, vcc_hi, v6
	v_add_u32_e32 v23, vcc_hi, v7
	v_add_u32_e32 v24, vcc_hi, v8
	v_add_u32_e32 v25, vcc_hi, v9
	v_add_u32_e32 v26, vcc_hi, v10
	v_add_u32_e32 v27, vcc_hi, v11
	v_add_u32_e32 v28, vcc_hi, v12
	v_add_u32_e32 v29, vcc_hi, v13
	v_add_u32_e32 v30, vcc_hi, v14
	v_add_u32_e32 v31, vcc_hi, v15
	v_add_u32_e32 v32, vcc_hi, v16
	v_add_u32_e32 v33, vcc_hi, v17
	v_add_u32_e32 v34, vcc_hi, v18
	v_add_u32_e32 v35, vcc_hi, v19
	s_add_u32 vcc_lo, vcc_lo, 1
	s_barrier
	s_add_u32 m0, s100, 0x8000
	s_nop 0
	global_load_lds_dwordx4 v20, s[26:27]
	s_add_u32 m0, s100, 0x8400
	s_nop 0
	global_load_lds_dwordx4 v21, s[26:27]
	s_add_u32 m0, s100, 0x9000
	s_nop 0
	global_load_lds_dwordx4 v22, s[26:27]
	s_add_u32 m0, s100, 0x9400
	s_nop 0
	global_load_lds_dwordx4 v23, s[26:27]
	s_add_u32 m0, s100, 0xa000
	s_nop 0
	global_load_lds_dwordx4 v24, s[26:27]
	s_add_u32 m0, s100, 0xa400
	s_nop 0
	global_load_lds_dwordx4 v25, s[26:27]
	s_add_u32 m0, s100, 0xb000
	s_nop 0
	global_load_lds_dwordx4 v26, s[26:27]
	s_add_u32 m0, s100, 0xb400
	s_nop 0
	global_load_lds_dwordx4 v27, s[26:27]
	s_waitcnt vmcnt(8)
	s_barrier
	s_add_u32 m0, s100, 0xc000
	s_nop 0
	global_load_lds_dwordx4 v28, s[38:39]
	s_add_u32 m0, s100, 0xc400
	s_nop 0
	global_load_lds_dwordx4 v29, s[38:39]
	s_add_u32 m0, s100, 0xd000
	s_nop 0
	global_load_lds_dwordx4 v30, s[38:39]
	s_add_u32 m0, s100, 0xd400
	s_nop 0
	global_load_lds_dwordx4 v31, s[38:39]
	s_add_u32 m0, s100, 0xe000
	s_nop 0
	global_load_lds_dwordx4 v32, s[38:39]
	s_add_u32 m0, s100, 0xe400
	s_nop 0
	global_load_lds_dwordx4 v33, s[38:39]
	s_add_u32 m0, s100, 0xf000
	s_nop 0
	global_load_lds_dwordx4 v34, s[38:39]
	s_add_u32 m0, s100, 0xf400
	s_nop 0
	global_load_lds_dwordx4 v35, s[38:39]
	s_add_u32 s24, s24, 0x100
	s_addc_u32 s25, s25, 0
	s_add_i32 s52, s52, 2
	s_cmp_le_i32 s52, s49
	s_cbranch_scc1 .Lpc_ptop_6
	s_setprio 0
	s_add_i32 s42, s42, 1
	s_mov_b32 s46, s44
	s_mov_b32 s47, s45
	s_cmp_eq_u32 s42, 3
	s_cbranch_scc0 .Lpc_pnd_6
	s_waitcnt vmcnt(0)
	s_branch .LBB0_276

.Lpc_pgo_3:
	s_nop 0
	s_sub_u32 s40, s40, s98
	s_subb_u32 s41, s41, 0
	s_sub_u32 s38, s38, s99
	s_subb_u32 s39, s39, 0
	s_bfe_u32 vcc_hi, s101, 0x80008
	s_add_u32 vcc_hi, vcc_hi, vcc_lo
	s_add_u32 m0, s42, -1
	s_and_b32 vcc_hi, vcc_hi, m0
	s_lshl_b32 vcc_hi, vcc_hi, 7
	v_add_u32_e32 v20, vcc_hi, v4
	v_add_u32_e32 v21, vcc_hi, v5
	v_add_u32_e32 v22, vcc_hi, v6
	v_add_u32_e32 v23, vcc_hi, v7
	v_add_u32_e32 v24, vcc_hi, v8
	v_add_u32_e32 v25, vcc_hi, v9
	v_add_u32_e32 v26, vcc_hi, v10
	v_add_u32_e32 v27, vcc_hi, v11
	v_add_u32_e32 v28, vcc_hi, v12
	v_add_u32_e32 v29, vcc_hi, v13
	v_add_u32_e32 v30, vcc_hi, v14
	v_add_u32_e32 v31, vcc_hi, v15
	v_add_u32_e32 v32, vcc_hi, v16
	v_add_u32_e32 v33, vcc_hi, v17
	v_add_u32_e32 v34, vcc_hi, v18
	v_add_u32_e32 v35, vcc_hi, v19
	s_add_u32 vcc_lo, vcc_lo, 1
	s_barrier
	s_add_u32 m0, s100, 0x0
	s_nop 0
	global_load_lds_dwordx4 v20, s[40:41]
	s_add_u32 m0, s100, 0x400
	s_nop 0
	global_load_lds_dwordx4 v21, s[40:41]
	s_add_u32 m0, s100, 0x1000
	s_nop 0
	global_load_lds_dwordx4 v22, s[40:41]
	s_add_u32 m0, s100, 0x1400
	s_nop 0
	global_load_lds_dwordx4 v23, s[40:41]
	s_add_u32 m0, s100, 0x2000
	s_nop 0
	global_load_lds_dwordx4 v24, s[40:41]
	s_add_u32 m0, s100, 0x2400
	s_nop 0
	global_load_lds_dwordx4 v25, s[40:41]
	s_add_u32 m0, s100, 0x3000
	s_nop 0
	global_load_lds_dwordx4 v26, s[40:41]
	s_add_u32 m0, s100, 0x3400
	s_nop 0
	global_load_lds_dwordx4 v27, s[40:41]
	s_waitcnt vmcnt(8)
	s_barrier
	s_add_u32 m0, s100, 0x4000
	s_nop 0
	global_load_lds_dwordx4 v28, s[38:39]
	s_add_u32 m0, s100, 0x4400
	s_nop 0
	global_load_lds_dwordx4 v29, s[38:39]
	s_add_u32 m0, s100, 0x5000
	s_nop 0
	global_load_lds_dwordx4 v30, s[38:39]
	s_add_u32 m0, s100, 0x5400
	s_nop 0
	global_load_lds_dwordx4 v31, s[38:39]
	s_add_u32 m0, s100, 0x6000
	s_nop 0
	global_load_lds_dwordx4 v32, s[38:39]
	s_add_u32 m0, s100, 0x6400
	s_nop 0
	global_load_lds_dwordx4 v33, s[38:39]
	s_add_u32 m0, s100, 0x7000
	s_nop 0
	global_load_lds_dwordx4 v34, s[38:39]
	s_add_u32 m0, s100, 0x7400
	s_nop 0
	global_load_lds_dwordx4 v35, s[38:39]
	s_bfe_u32 vcc_hi, s101, 0x80008
	s_add_u32 vcc_hi, vcc_hi, vcc_lo
	s_add_u32 m0, s42, -1
	s_and_b32 vcc_hi, vcc_hi, m0
	s_lshl_b32 vcc_hi, vcc_hi, 7
	v_add_u32_e32 v20, vcc_hi, v4
	v_add_u32_e32 v21, vcc_hi, v5
	v_add_u32_e32 v22, vcc_hi, v6
	v_add_u32_e32 v23, vcc_hi, v7
	v_add_u32_e32 v24, vcc_hi, v8
	v_add_u32_e32 v25, vcc_hi, v9
	v_add_u32_e32 v26, vcc_hi, v10
	v_add_u32_e32 v27, vcc_hi, v11
	v_add_u32_e32 v28, vcc_hi, v12
	v_add_u32_e32 v29, vcc_hi, v13
	v_add_u32_e32 v30, vcc_hi, v14
	v_add_u32_e32 v31, vcc_hi, v15
	v_add_u32_e32 v32, vcc_hi, v16
	v_add_u32_e32 v33, vcc_hi, v17
	v_add_u32_e32 v34, vcc_hi, v18
	v_add_u32_e32 v35, vcc_hi, v19
	s_add_u32 vcc_lo, vcc_lo, 1
	s_barrier
	s_add_u32 m0, s100, 0x8000
	s_nop 0
	global_load_lds_dwordx4 v20, s[40:41]
	s_add_u32 m0, s100, 0x8400
	s_nop 0
	global_load_lds_dwordx4 v21, s[40:41]
	s_add_u32 m0, s100, 0x9000
	s_nop 0
	global_load_lds_dwordx4 v22, s[40:41]
	s_add_u32 m0, s100, 0x9400
	s_nop 0
	global_load_lds_dwordx4 v23, s[40:41]
	s_add_u32 m0, s100, 0xa000
	s_nop 0
	global_load_lds_dwordx4 v24, s[40:41]
	s_add_u32 m0, s100, 0xa400
	s_nop 0
	global_load_lds_dwordx4 v25, s[40:41]
	s_add_u32 m0, s100, 0xb000
	s_nop 0
	global_load_lds_dwordx4 v26, s[40:41]
	s_add_u32 m0, s100, 0xb400
	s_nop 0
	global_load_lds_dwordx4 v27, s[40:41]
	s_waitcnt vmcnt(8)
	s_barrier
	s_add_u32 m0, s100, 0xc000
	s_nop 0
	global_load_lds_dwordx4 v28, s[38:39]
	s_add_u32 m0, s100, 0xc400
	s_nop 0
	global_load_lds_dwordx4 v29, s[38:39]
	s_add_u32 m0, s100, 0xd000
	s_nop 0
	global_load_lds_dwordx4 v30, s[38:39]
	s_add_u32 m0, s100, 0xd400
	s_nop 0
	global_load_lds_dwordx4 v31, s[38:39]
	s_add_u32 m0, s100, 0xe000
	s_nop 0
	global_load_lds_dwordx4 v32, s[38:39]
	s_add_u32 m0, s100, 0xe400
	s_nop 0
	global_load_lds_dwordx4 v33, s[38:39]
	s_add_u32 m0, s100, 0xf000
	s_nop 0
	global_load_lds_dwordx4 v34, s[38:39]
	s_add_u32 m0, s100, 0xf400
	s_nop 0
	global_load_lds_dwordx4 v35, s[38:39]
	s_add_u32 s34, s34, 0x100
	s_addc_u32 s35, s35, 0
	s_add_i32 s96, s96, 2
	s_cmp_le_i32 s96, s47
	s_cbranch_scc1 .Lpc_ptop_3
	s_setprio 0
	s_mov_b32 s97, s5
	s_movk_i32 s96, 0x43ff
	s_mov_b32 s55, s49
	s_mov_b32 s53, s1
	s_and_b64 vcc, exec, s[26:27]
	v_mov_b64_e32 v[146:147], v[142:143]
	v_mov_b64_e32 v[144:145], v[140:141]
	s_cbranch_vccz .Lpc_pnd_3
	s_waitcnt vmcnt(0)
	s_branch .LBB0_319

.Lpc_pgo_4:
	s_nop 0
	s_sub_u32 s40, s40, s98
	s_subb_u32 s41, s41, 0
	s_sub_u32 s38, s38, s99
	s_subb_u32 s39, s39, 0
	s_bfe_u32 vcc_hi, s101, 0x80008
	s_add_u32 vcc_hi, vcc_hi, vcc_lo
	s_add_u32 m0, s42, -1
	s_and_b32 vcc_hi, vcc_hi, m0
	s_lshl_b32 vcc_hi, vcc_hi, 7
	v_add_u32_e32 v20, vcc_hi, v4
	v_add_u32_e32 v21, vcc_hi, v5
	v_add_u32_e32 v22, vcc_hi, v6
	v_add_u32_e32 v23, vcc_hi, v7
	v_add_u32_e32 v24, vcc_hi, v8
	v_add_u32_e32 v25, vcc_hi, v9
	v_add_u32_e32 v26, vcc_hi, v10
	v_add_u32_e32 v27, vcc_hi, v11
	v_add_u32_e32 v28, vcc_hi, v12
	v_add_u32_e32 v29, vcc_hi, v13
	v_add_u32_e32 v30, vcc_hi, v14
	v_add_u32_e32 v31, vcc_hi, v15
	v_add_u32_e32 v32, vcc_hi, v16
	v_add_u32_e32 v33, vcc_hi, v17
	v_add_u32_e32 v34, vcc_hi, v18
	v_add_u32_e32 v35, vcc_hi, v19
	s_add_u32 vcc_lo, vcc_lo, 1
	s_barrier
	s_add_u32 m0, s100, 0x0
	s_nop 0
	global_load_lds_dwordx4 v20, s[40:41]
	s_add_u32 m0, s100, 0x400
	s_nop 0
	global_load_lds_dwordx4 v21, s[40:41]
	s_add_u32 m0, s100, 0x1000
	s_nop 0
	global_load_lds_dwordx4 v22, s[40:41]
	s_add_u32 m0, s100, 0x1400
	s_nop 0
	global_load_lds_dwordx4 v23, s[40:41]
	s_add_u32 m0, s100, 0x2000
	s_nop 0
	global_load_lds_dwordx4 v24, s[40:41]
	s_add_u32 m0, s100, 0x2400
	s_nop 0
	global_load_lds_dwordx4 v25, s[40:41]
	s_add_u32 m0, s100, 0x3000
	s_nop 0
	global_load_lds_dwordx4 v26, s[40:41]
	s_add_u32 m0, s100, 0x3400
	s_nop 0
	global_load_lds_dwordx4 v27, s[40:41]
	s_waitcnt vmcnt(8)
	s_barrier
	s_add_u32 m0, s100, 0x4000
	s_nop 0
	global_load_lds_dwordx4 v28, s[38:39]
	s_add_u32 m0, s100, 0x4400
	s_nop 0
	global_load_lds_dwordx4 v29, s[38:39]
	s_add_u32 m0, s100, 0x5000
	s_nop 0
	global_load_lds_dwordx4 v30, s[38:39]
	s_add_u32 m0, s100, 0x5400
	s_nop 0
	global_load_lds_dwordx4 v31, s[38:39]
	s_add_u32 m0, s100, 0x6000
	s_nop 0
	global_load_lds_dwordx4 v32, s[38:39]
	s_add_u32 m0, s100, 0x6400
	s_nop 0
	global_load_lds_dwordx4 v33, s[38:39]
	s_add_u32 m0, s100, 0x7000
	s_nop 0
	global_load_lds_dwordx4 v34, s[38:39]
	s_add_u32 m0, s100, 0x7400
	s_nop 0
	global_load_lds_dwordx4 v35, s[38:39]
	s_bfe_u32 vcc_hi, s101, 0x80008
	s_add_u32 vcc_hi, vcc_hi, vcc_lo
	s_add_u32 m0, s42, -1
	s_and_b32 vcc_hi, vcc_hi, m0
	s_lshl_b32 vcc_hi, vcc_hi, 7
	v_add_u32_e32 v20, vcc_hi, v4
	v_add_u32_e32 v21, vcc_hi, v5
	v_add_u32_e32 v22, vcc_hi, v6
	v_add_u32_e32 v23, vcc_hi, v7
	v_add_u32_e32 v24, vcc_hi, v8
	v_add_u32_e32 v25, vcc_hi, v9
	v_add_u32_e32 v26, vcc_hi, v10
	v_add_u32_e32 v27, vcc_hi, v11
	v_add_u32_e32 v28, vcc_hi, v12
	v_add_u32_e32 v29, vcc_hi, v13
	v_add_u32_e32 v30, vcc_hi, v14
	v_add_u32_e32 v31, vcc_hi, v15
	v_add_u32_e32 v32, vcc_hi, v16
	v_add_u32_e32 v33, vcc_hi, v17
	v_add_u32_e32 v34, vcc_hi, v18
	v_add_u32_e32 v35, vcc_hi, v19
	s_add_u32 vcc_lo, vcc_lo, 1
	s_barrier
	s_add_u32 m0, s100, 0x8000
	s_nop 0
	global_load_lds_dwordx4 v20, s[40:41]
	s_add_u32 m0, s100, 0x8400
	s_nop 0
	global_load_lds_dwordx4 v21, s[40:41]
	s_add_u32 m0, s100, 0x9000
	s_nop 0
	global_load_lds_dwordx4 v22, s[40:41]
	s_add_u32 m0, s100, 0x9400
	s_nop 0
	global_load_lds_dwordx4 v23, s[40:41]
	s_add_u32 m0, s100, 0xa000
	s_nop 0
	global_load_lds_dwordx4 v24, s[40:41]
	s_add_u32 m0, s100, 0xa400
	s_nop 0
	global_load_lds_dwordx4 v25, s[40:41]
	s_add_u32 m0, s100, 0xb000
	s_nop 0
	global_load_lds_dwordx4 v26, s[40:41]
	s_add_u32 m0, s100, 0xb400
	s_nop 0
	global_load_lds_dwordx4 v27, s[40:41]
	s_waitcnt vmcnt(8)
	s_barrier
	s_add_u32 m0, s100, 0xc000
	s_nop 0
	global_load_lds_dwordx4 v28, s[38:39]
	s_add_u32 m0, s100, 0xc400
	s_nop 0
	global_load_lds_dwordx4 v29, s[38:39]
	s_add_u32 m0, s100, 0xd000
	s_nop 0
	global_load_lds_dwordx4 v30, s[38:39]
	s_add_u32 m0, s100, 0xd400
	s_nop 0
	global_load_lds_dwordx4 v31, s[38:39]
	s_add_u32 m0, s100, 0xe000
	s_nop 0
	global_load_lds_dwordx4 v32, s[38:39]
	s_add_u32 m0, s100, 0xe400
	s_nop 0
	global_load_lds_dwordx4 v33, s[38:39]
	s_add_u32 m0, s100, 0xf000
	s_nop 0
	global_load_lds_dwordx4 v34, s[38:39]
	s_add_u32 m0, s100, 0xf400
	s_nop 0
	global_load_lds_dwordx4 v35, s[38:39]
	s_add_u32 s34, s34, 0x100
	s_addc_u32 s35, s35, 0
	s_add_i32 s55, s55, 2
	s_cmp_le_i32 s55, s47
	s_cbranch_scc1 .Lpc_ptop_4
	s_setprio 0
	s_mov_b32 s53, s49
	s_mov_b32 s52, s1
	v_mov_b64_e32 v[146:147], v[142:143]
	v_mov_b64_e32 v[144:145], v[140:141]
	s_and_b64 vcc, exec, s[26:27]
	s_cbranch_vccz .Lpc_pnd_4
	s_waitcnt vmcnt(0)
	s_branch .LBB0_342

.Lpc_pgo_1:
	s_nop 0
	s_sub_u32 s40, s40, s98
	s_subb_u32 s41, s41, 0
	s_sub_u32 s38, s38, s99
	s_subb_u32 s39, s39, 0
	s_bfe_u32 vcc_hi, s101, 0x80008
	s_add_u32 vcc_hi, vcc_hi, vcc_lo
	s_add_u32 m0, s42, -1
	s_and_b32 vcc_hi, vcc_hi, m0
	s_lshl_b32 vcc_hi, vcc_hi, 7
	v_add_u32_e32 v20, vcc_hi, v4
	v_add_u32_e32 v21, vcc_hi, v5
	v_add_u32_e32 v22, vcc_hi, v6
	v_add_u32_e32 v23, vcc_hi, v7
	v_add_u32_e32 v24, vcc_hi, v8
	v_add_u32_e32 v25, vcc_hi, v9
	v_add_u32_e32 v26, vcc_hi, v10
	v_add_u32_e32 v27, vcc_hi, v11
	v_add_u32_e32 v28, vcc_hi, v12
	v_add_u32_e32 v29, vcc_hi, v13
	v_add_u32_e32 v30, vcc_hi, v14
	v_add_u32_e32 v31, vcc_hi, v15
	v_add_u32_e32 v32, vcc_hi, v16
	v_add_u32_e32 v33, vcc_hi, v17
	v_add_u32_e32 v34, vcc_hi, v18
	v_add_u32_e32 v35, vcc_hi, v19
	s_add_u32 vcc_lo, vcc_lo, 1
	s_barrier
	s_add_u32 m0, s100, 0x0
	s_nop 0
	global_load_lds_dwordx4 v20, s[40:41]
	s_add_u32 m0, s100, 0x400
	s_nop 0
	global_load_lds_dwordx4 v21, s[40:41]
	s_add_u32 m0, s100, 0x1000
	s_nop 0
	global_load_lds_dwordx4 v22, s[40:41]
	s_add_u32 m0, s100, 0x1400
	s_nop 0
	global_load_lds_dwordx4 v23, s[40:41]
	s_add_u32 m0, s100, 0x2000
	s_nop 0
	global_load_lds_dwordx4 v24, s[40:41]
	s_add_u32 m0, s100, 0x2400
	s_nop 0
	global_load_lds_dwordx4 v25, s[40:41]
	s_add_u32 m0, s100, 0x3000
	s_nop 0
	global_load_lds_dwordx4 v26, s[40:41]
	s_add_u32 m0, s100, 0x3400
	s_nop 0
	global_load_lds_dwordx4 v27, s[40:41]
	s_waitcnt vmcnt(8)
	s_barrier
	s_add_u32 m0, s100, 0x4000
	s_nop 0
	global_load_lds_dwordx4 v28, s[38:39]
	s_add_u32 m0, s100, 0x4400
	s_nop 0
	global_load_lds_dwordx4 v29, s[38:39]
	s_add_u32 m0, s100, 0x5000
	s_nop 0
	global_load_lds_dwordx4 v30, s[38:39]
	s_add_u32 m0, s100, 0x5400
	s_nop 0
	global_load_lds_dwordx4 v31, s[38:39]
	s_add_u32 m0, s100, 0x6000
	s_nop 0
	global_load_lds_dwordx4 v32, s[38:39]
	s_add_u32 m0, s100, 0x6400
	s_nop 0
	global_load_lds_dwordx4 v33, s[38:39]
	s_add_u32 m0, s100, 0x7000
	s_nop 0
	global_load_lds_dwordx4 v34, s[38:39]
	s_add_u32 m0, s100, 0x7400
	s_nop 0
	global_load_lds_dwordx4 v35, s[38:39]
	s_bfe_u32 vcc_hi, s101, 0x80008
	s_add_u32 vcc_hi, vcc_hi, vcc_lo
	s_add_u32 m0, s42, -1
	s_and_b32 vcc_hi, vcc_hi, m0
	s_lshl_b32 vcc_hi, vcc_hi, 7
	v_add_u32_e32 v20, vcc_hi, v4
	v_add_u32_e32 v21, vcc_hi, v5
	v_add_u32_e32 v22, vcc_hi, v6
	v_add_u32_e32 v23, vcc_hi, v7
	v_add_u32_e32 v24, vcc_hi, v8
	v_add_u32_e32 v25, vcc_hi, v9
	v_add_u32_e32 v26, vcc_hi, v10
	v_add_u32_e32 v27, vcc_hi, v11
	v_add_u32_e32 v28, vcc_hi, v12
	v_add_u32_e32 v29, vcc_hi, v13
	v_add_u32_e32 v30, vcc_hi, v14
	v_add_u32_e32 v31, vcc_hi, v15
	v_add_u32_e32 v32, vcc_hi, v16
	v_add_u32_e32 v33, vcc_hi, v17
	v_add_u32_e32 v34, vcc_hi, v18
	v_add_u32_e32 v35, vcc_hi, v19
	s_add_u32 vcc_lo, vcc_lo, 1
	s_barrier
	s_add_u32 m0, s100, 0x8000
	s_nop 0
	global_load_lds_dwordx4 v20, s[40:41]
	s_add_u32 m0, s100, 0x8400
	s_nop 0
	global_load_lds_dwordx4 v21, s[40:41]
	s_add_u32 m0, s100, 0x9000
	s_nop 0
	global_load_lds_dwordx4 v22, s[40:41]
	s_add_u32 m0, s100, 0x9400
	s_nop 0
	global_load_lds_dwordx4 v23, s[40:41]
	s_add_u32 m0, s100, 0xa000
	s_nop 0
	global_load_lds_dwordx4 v24, s[40:41]
	s_add_u32 m0, s100, 0xa400
	s_nop 0
	global_load_lds_dwordx4 v25, s[40:41]
	s_add_u32 m0, s100, 0xb000
	s_nop 0
	global_load_lds_dwordx4 v26, s[40:41]
	s_add_u32 m0, s100, 0xb400
	s_nop 0
	global_load_lds_dwordx4 v27, s[40:41]
	s_waitcnt vmcnt(8)
	s_barrier
	s_add_u32 m0, s100, 0xc000
	s_nop 0
	global_load_lds_dwordx4 v28, s[38:39]
	s_add_u32 m0, s100, 0xc400
	s_nop 0
	global_load_lds_dwordx4 v29, s[38:39]
	s_add_u32 m0, s100, 0xd000
	s_nop 0
	global_load_lds_dwordx4 v30, s[38:39]
	s_add_u32 m0, s100, 0xd400
	s_nop 0
	global_load_lds_dwordx4 v31, s[38:39]
	s_add_u32 m0, s100, 0xe000
	s_nop 0
	global_load_lds_dwordx4 v32, s[38:39]
	s_add_u32 m0, s100, 0xe400
	s_nop 0
	global_load_lds_dwordx4 v33, s[38:39]
	s_add_u32 m0, s100, 0xf000
	s_nop 0
	global_load_lds_dwordx4 v34, s[38:39]
	s_add_u32 m0, s100, 0xf400
	s_nop 0
	global_load_lds_dwordx4 v35, s[38:39]
	s_add_u32 s34, s34, 0x100
	s_addc_u32 s35, s35, 0
	s_add_i32 s53, s53, 2
	s_cmp_le_i32 s53, s47
	s_cbranch_scc1 .Lpc_ptop_1
	s_setprio 0
	s_movk_i32 s4, 0x3100
	s_mov_b32 s52, s48
	s_mov_b32 s49, s1
	s_and_b64 vcc, exec, s[26:27]
	v_mov_b64_e32 v[146:147], v[142:143]
	v_mov_b64_e32 v[144:145], v[140:141]
	s_cbranch_vccz .Lpc_pnd_1
	s_waitcnt vmcnt(0)
	s_branch .LBB0_965
